# v28 without the nt hint on the hosted 16-B row loads (both 64-B halves of a line are read by back-to-back instructions)
# baseline (speedup 1.0000x reference)
; template <int NB>
; __device__ __forceinline__ void p0_batch(int it0, int stride, int lane, const P0Ptrs& a) {
;     ...
;     for (int q = 0; q < NB; ++q) { const bool ok = it0 < NFAST / 4; d[q] = p0_desc(p0_super(ok ? it0 : 0, q), lane, a); if (!ok) d[q].dst = nullptr;
; #pragma unroll
;         for (int i = 0; i < 8; ++i) v[q][i] = __builtin_nontemporal_load((const f32x4*)(d[q].src + (size_t)i * d[q].nsrc));
;         const float* kp = d[q].ks ? d[q].ks : a.ffn_g;
;         s0[q] = *(const f32x4*)(kp); s1[q] = *(const f32x4*)(kp + 4); }
.Lcv_wad:
	s_barrier
	global_load_lds_dwordx4 v[100:101], off
	v_lshl_add_u64 v[100:101], v[112:113], 0, s[38:39]
	s_add_i32 m0, s78, 0x2000
	v_lshl_add_u64 v[136:137], s[28:29], 0, v[144:145]
	global_load_lds_dwordx4 v[100:101], off
	v_lshl_add_u64 v[100:101], v[136:137], 0, s[40:41]
	s_add_i32 m0, s78, 0x4000
	v_lshl_add_u64 v[134:135], s[28:29], 0, v[148:149]
	global_load_lds_dwordx4 v[100:101], off
	v_lshl_add_u64 v[100:101], v[134:135], 0, s[42:43]
	s_mov_b32 m0, s58
	global_load_lds_dwordx4 v[100:101], off
	v_lshl_add_u64 v[100:101], v[134:135], 0, s[44:45]
	s_mov_b32 m0, s77
	global_load_lds_dwordx4 v[100:101], off
	s_cmp_gt_u32 s87, 20
	s_cbranch_scc1 .Lcv_done
	s_cmp_gt_u32 s87, 19
	s_cbranch_scc1 .Lcv_inc
	s_lshl_b32 s98, s90, 4
	global_load_dwordx4 v[238:241], v79, s[88:89]
	global_load_dwordx4 v[242:245], v79, s[88:89] offset:64
	global_load_dword v237, v80, s[94:95]
	s_add_u32 s88, s88, s98
	s_addc_u32 s89, s89, 0
	s_add_u32 s94, s94, 64
	s_addc_u32 s95, s95, 0
	s_and_b32 s98, s87, 3
	s_cmp_lg_u32 s98, 3
	s_cbranch_scc1 .Lcv_inc
	s_cmp_gt_u32 s87, 18
	s_cbranch_scc1 .Lcv_inc
	s_add_i32 s99, s32, 1
	s_movk_i32 s98, 0x78
	s_cmp_lt_u32 s99, 7
	s_cselect_b32 s98, 0x60, s98
	s_cmp_eq_u32 s99, 0
	s_cselect_b32 s98, 0x50, s98
	s_cselect_b32 s99, 0, 0x58
	s_load_dwordx2 s[88:89], s[100:101], s98
	s_cmp_eq_u32 s99, 0
	s_cbranch_scc0 .Lcv_s1b_s
	s_bfe_u32 s99, s2, 0x50003
	s_cmp_lt_u32 s99, 16
	s_cselect_b32 s99, 64, 0x48
